# pre-pass state_pool@W_mix mm_tile jobs: all 16 K-chunk loads issued at job start (same de-serialization as the W' jobs)
# baseline (speedup 1.0000x reference)
; #define LAS __attribute__((address_space(3)))
; template <bool TRANS>
; __device__ __forceinline__ void mm_tile(LAS float* sm, int tid, const float* __restrict__ A, int lda, int r0, int rmax, int acol0, const float* __restrict__ Wm, int d0, void* dstv, int ldd, int n0, unsigned* cmaxw) {
;     ...
;     for (int i = 0; i < 2; ++i) { const int idx = tid + i * 512, rr = idx >> 4, c4 = idx & 15;
;         va[i] = (f32x4){0.f, 0.f, 0.f, 0.f}; if (r0 + rr < rmax) va[i] = *(const f32x4*)(A + (size_t)(r0 + rr) * lda + acol0 + c4 * 4);
;         vb[i] = *(const f32x4*)(Wm + (size_t)rr * 256 + d0 + c4 * 4); }
;     for (int cc = 0; cc < 256; cc += 64) {
; #pragma unroll
;         for (int i = 0; i < 2; ++i) { const int idx = tid + i * 512, rr = idx >> 4, c4 = idx & 15;
;             *(LAS f32x4*)(As + rr * 68 + c4 * 4) = va[i];
;             LAS float* q = Bt + (c4 * 4) * 68 + rr; q[0] = vb[i][0]; q[68] = vb[i][1]; q[136] = vb[i][2]; q[204] = vb[i][3]; }
;         __syncthreads();
;         if (cc + 64 < 256) {
; #pragma unroll
;             for (int i = 0; i < 2; ++i) { const int idx = tid + i * 512, rr = idx >> 4, c4 = idx & 15;
;                 va[i] = (f32x4){0.f, 0.f, 0.f, 0.f}; if (r0 + rr < rmax) va[i] = *(const f32x4*)(A + (size_t)(r0 + rr) * lda + acol0 + cc + 64 + c4 * 4);
;                 vb[i] = *(const f32x4*)(Wm + (size_t)(cc + 64 + rr) * 256 + d0 + c4 * 4); } }
.LBB0_46:
	s_or_b64 exec, exec, s[6:7]
	v_lshl_add_u64 v[10:11], v[52:53], 0, v[34:35]
	global_load_dwordx4 v[22:25], v[10:11], off
	v_lshlrev_b64 v[168:169], 12, v[54:55]
	v_lshl_add_u64 v[168:169], s[4:5], 0, v[168:169]
	v_lshl_add_u64 v[168:169], v[168:169], 0, v[26:27]
	v_lshlrev_b64 v[170:171], 12, v[56:57]
	v_lshl_add_u64 v[170:171], s[4:5], 0, v[170:171]
	v_lshl_add_u64 v[170:171], v[170:171], 0, v[26:27]
	v_mov_b64_e32 v[120:121], 0
	v_mov_b64_e32 v[122:123], 0
	v_mov_b64_e32 v[128:129], 0
	v_mov_b64_e32 v[130:131], 0
	s_and_saveexec_b64 s[98:99], vcc
	global_load_dwordx4 v[120:123], v[168:169], off offset:256
	s_mov_b64 exec, s[98:99]
	v_lshl_add_u64 v[172:173], v[52:53], 0, v[38:39]
	global_load_dwordx4 v[124:127], v[172:173], off
	s_and_saveexec_b64 s[98:99], s[2:3]
	global_load_dwordx4 v[128:131], v[170:171], off offset:256
	s_mov_b64 exec, s[98:99]
	v_lshl_add_u64 v[172:173], v[52:53], 0, v[40:41]
	global_load_dwordx4 v[132:135], v[172:173], off
	v_mov_b64_e32 v[136:137], 0
	v_mov_b64_e32 v[138:139], 0
	v_mov_b64_e32 v[144:145], 0
	v_mov_b64_e32 v[146:147], 0
	s_and_saveexec_b64 s[98:99], vcc
	global_load_dwordx4 v[136:139], v[168:169], off offset:512
	s_mov_b64 exec, s[98:99]
	v_lshl_add_u64 v[172:173], v[52:53], 0, v[42:43]
	global_load_dwordx4 v[140:143], v[172:173], off
	s_and_saveexec_b64 s[98:99], s[2:3]
	global_load_dwordx4 v[144:147], v[170:171], off offset:512
	s_mov_b64 exec, s[98:99]
	v_lshl_add_u64 v[172:173], v[52:53], 0, v[44:45]
	global_load_dwordx4 v[148:151], v[172:173], off
	v_mov_b64_e32 v[152:153], 0
	v_mov_b64_e32 v[154:155], 0
	v_mov_b64_e32 v[160:161], 0
	v_mov_b64_e32 v[162:163], 0
	s_and_saveexec_b64 s[98:99], vcc
	global_load_dwordx4 v[152:155], v[168:169], off offset:768
	s_mov_b64 exec, s[98:99]
	v_lshl_add_u64 v[172:173], v[52:53], 0, v[46:47]
	global_load_dwordx4 v[156:159], v[172:173], off
	s_and_saveexec_b64 s[98:99], s[2:3]
	global_load_dwordx4 v[160:163], v[170:171], off offset:768
	s_mov_b64 exec, s[98:99]
	v_lshl_add_u64 v[172:173], v[52:53], 0, v[48:49]
	global_load_dwordx4 v[164:167], v[172:173], off
	v_add_u32_e32 v61, 0x4400, v1
	v_add_u32_e32 v60, 0x4400, v29
	v_mov_b32_e32 v10, 0
	v_mov_b32_e32 v14, 0
	v_mov_b32_e32 v15, 0
	v_mov_b32_e32 v16, 0
	v_mov_b32_e32 v17, 0
	s_waitcnt vmcnt(14)
	ds_write_b128 v37, v[2:5]
	s_waitcnt vmcnt(13)
	ds_write2_b32 v61, v6, v7 offset1:68
	ds_write2_b32 v61, v8, v9 offset0:136 offset1:204
	ds_write_b128 v58, v[18:21]
	s_waitcnt vmcnt(12)
	ds_write2_b32 v60, v22, v23 offset1:68
	ds_write2_b32 v60, v24, v25 offset0:136 offset1:204
	s_waitcnt lgkmcnt(0)
	s_barrier
	s_and_saveexec_b64 s[6:7], vcc
	s_cbranch_execz .LBB0_48
	v_lshlrev_b64 v[2:3], 12, v[54:55]
	v_lshl_add_u64 v[2:3], s[4:5], 0, v[2:3]
	v_lshl_add_u64 v[2:3], v[2:3], 0, v[26:27]
.LBB0_48:
	s_or_b64 exec, exec, s[6:7]
	v_lshl_add_u64 v[2:3], v[52:53], 0, v[38:39]
	v_mov_b32_e32 v11, 0
	v_mov_b32_e32 v12, 0
	v_mov_b32_e32 v13, 0
	s_and_saveexec_b64 s[6:7], s[2:3]
	s_cbranch_execz .LBB0_50
	v_lshlrev_b64 v[2:3], 12, v[56:57]
	v_lshl_add_u64 v[2:3], s[4:5], 0, v[2:3]
	v_lshl_add_u64 v[2:3], v[2:3], 0, v[26:27]
.LBB0_50:
	s_or_b64 exec, exec, s[6:7]
	v_lshl_add_u64 v[2:3], v[52:53], 0, v[40:41]
	ds_read_b128 v[62:65], v36
	ds_read_b128 v[66:69], v36 offset:16
	ds_read_b128 v[70:73], v59 offset:17408
	ds_read_b128 v[74:77], v59 offset:17424
	ds_read_b128 v[78:81], v59 offset:21760
	ds_read_b128 v[82:85], v59 offset:21776
	ds_read_b128 v[86:89], v36 offset:128
	ds_read_b128 v[90:93], v36 offset:144
	ds_read_b128 v[94:97], v59 offset:17536
	ds_read_b128 v[98:101], v59 offset:17552
	ds_read_b128 v[102:105], v59 offset:21888
	ds_read_b128 v[106:109], v59 offset:21904
	s_waitcnt lgkmcnt(0)
	s_barrier
	s_waitcnt vmcnt(10)
	ds_write_b128 v37, v[120:123]
	s_waitcnt vmcnt(9)
	ds_write2_b32 v61, v124, v125 offset1:68
	ds_write2_b32 v61, v126, v127 offset0:136 offset1:204
	ds_write_b128 v58, v[128:131]
	v_cvt_pk_bf16_f32 v10, v62, v63
	v_cvt_pk_bf16_f32 v11, v64, v65
	v_cvt_pk_bf16_f32 v12, v66, v67
	v_cvt_pk_bf16_f32 v13, v68, v69
	v_cvt_pk_bf16_f32 v14, v70, v71
	v_cvt_pk_bf16_f32 v15, v72, v73
	v_cvt_pk_bf16_f32 v16, v74, v75
	v_cvt_pk_bf16_f32 v17, v76, v77
	v_cvt_pk_bf16_f32 v18, v78, v79
	v_cvt_pk_bf16_f32 v19, v80, v81
	v_cvt_pk_bf16_f32 v20, v82, v83
	v_cvt_pk_bf16_f32 v21, v84, v85
	v_cvt_pk_bf16_f32 v62, v86, v87
	v_cvt_pk_bf16_f32 v63, v88, v89
	v_cvt_pk_bf16_f32 v64, v90, v91
	v_cvt_pk_bf16_f32 v65, v92, v93
	v_mfma_f32_16x16x32_bf16 v[14:17], v[10:13], v[14:17], 0
	v_cvt_pk_bf16_f32 v66, v94, v95
	v_cvt_pk_bf16_f32 v67, v96, v97
	v_cvt_pk_bf16_f32 v68, v98, v99
	v_mfma_f32_16x16x32_bf16 v[18:21], v[10:13], v[18:21], 0
	v_cvt_pk_bf16_f32 v69, v100, v101
	v_cvt_pk_bf16_f32 v70, v102, v103
	v_cvt_pk_bf16_f32 v71, v104, v105
	v_cvt_pk_bf16_f32 v72, v106, v107
	v_cvt_pk_bf16_f32 v73, v108, v109
	v_mfma_f32_16x16x32_bf16 v[10:13], v[62:65], v[66:69], v[14:17]
	v_mov_b32_e32 v2, 0
	v_mov_b32_e32 v6, 0
	v_mov_b32_e32 v7, 0
	v_mfma_f32_16x16x32_bf16 v[14:17], v[62:65], v[70:73], v[18:21]
	v_mov_b32_e32 v8, 0
	v_mov_b32_e32 v9, 0
	s_waitcnt vmcnt(8)
	ds_write2_b32 v60, v132, v133 offset1:68
	ds_write2_b32 v60, v134, v135 offset0:136 offset1:204
	s_waitcnt lgkmcnt(0)
	s_barrier
	s_and_saveexec_b64 s[6:7], vcc
	s_cbranch_execz .LBB0_52
	v_lshlrev_b64 v[4:5], 12, v[54:55]
	v_lshl_add_u64 v[4:5], s[4:5], 0, v[4:5]
	v_lshl_add_u64 v[4:5], v[4:5], 0, v[26:27]
.LBB0_52:
	s_or_b64 exec, exec, s[6:7]
	v_lshl_add_u64 v[4:5], v[52:53], 0, v[42:43]
	v_mov_b32_e32 v22, 0
	v_mov_b32_e32 v23, 0
	v_mov_b32_e32 v24, 0
	v_mov_b32_e32 v25, 0
	s_and_saveexec_b64 s[6:7], s[2:3]
	s_cbranch_execz .LBB0_54
	v_lshlrev_b64 v[4:5], 12, v[56:57]
	v_lshl_add_u64 v[4:5], s[4:5], 0, v[4:5]
	v_lshl_add_u64 v[4:5], v[4:5], 0, v[26:27]
; #define LAS __attribute__((address_space(3)))
; template <bool TRANS>
; __device__ __forceinline__ void mm_tile(LAS float* sm, int tid, const float* __restrict__ A, int lda, int r0, int rmax, int acol0, const float* __restrict__ Wm, int d0, void* dstv, int ldd, int n0, unsigned* cmaxw) {
;     ...
;     for (int cc = 0; cc < 256; cc += 64) {
; #pragma unroll
;         for (int i = 0; i < 2; ++i) { const int idx = tid + i * 512, rr = idx >> 4, c4 = idx & 15;
;             *(LAS f32x4*)(As + rr * 68 + c4 * 4) = va[i];
;             LAS float* q = Bt + (c4 * 4) * 68 + rr; q[0] = vb[i][0]; q[68] = vb[i][1]; q[136] = vb[i][2]; q[204] = vb[i][3]; }
;         __syncthreads();
;         if (cc + 64 < 256) {
; #pragma unroll
;             for (int i = 0; i < 2; ++i) { const int idx = tid + i * 512, rr = idx >> 4, c4 = idx & 15;
;                 va[i] = (f32x4){0.f, 0.f, 0.f, 0.f}; if (r0 + rr < rmax) va[i] = *(const f32x4*)(A + (size_t)(r0 + rr) * lda + acol0 + cc + 64 + c4 * 4);
;                 vb[i] = *(const f32x4*)(Wm + (size_t)(cc + 64 + rr) * 256 + d0 + c4 * 4); } }
; #pragma unroll
;         for (int ks = 0; ks < 2; ++ks) {
;             const LAS float* ap = As + (br * 16 + fr) * 68 + ks * 32 + fq * 8;
;             const f32x4 a0 = *(const LAS f32x4*)ap, a1 = *(const LAS f32x4*)(ap + 4);
;             u32x4 aw; aw.x = pk_bf16(a0[0], a0[1]); aw.y = pk_bf16(a0[2], a0[3]); aw.z = pk_bf16(a1[0], a1[1]); aw.w = pk_bf16(a1[2], a1[3]);
;             const bf16x8 af = __builtin_bit_cast(bf16x8, aw);
; #pragma unroll
;             for (int bb = 0; bb < 2; ++bb) {
;                 const LAS float* bp = Bt + ((bc0 + bb) * 16 + fr) * 68 + ks * 32 + fq * 8;
;                 const f32x4 b0 = *(const LAS f32x4*)bp, b1 = *(const LAS f32x4*)(bp + 4);
;                 u32x4 bw; bw.x = pk_bf16(b0[0], b0[1]); bw.y = pk_bf16(b0[2], b0[3]); bw.z = pk_bf16(b1[0], b1[1]); bw.w = pk_bf16(b1[2], b1[3]);
;                 const bf16x8 bf = __builtin_bit_cast(bf16x8, bw);
;                 if (bb == 0) acc0 = __builtin_amdgcn_mfma_f32_16x16x32_bf16(af, bf, acc0, 0, 0, 0);
;                 else acc1 = __builtin_amdgcn_mfma_f32_16x16x32_bf16(af, bf, acc1, 0, 0, 0);
;             }
;         }
;         __syncthreads();
;     }
; #pragma unroll
;     for (int bb = 0; bb < 2; ++bb) { const f32x4 cacc = bb ? acc1 : acc0; const int d = (bc0 + bb) * 16 + fr, rl = br * 16 + fq * 4;
.LBB0_54:
	s_or_b64 exec, exec, s[6:7]
	v_lshl_add_u64 v[4:5], v[52:53], 0, v[44:45]
	ds_read_b128 v[66:69], v36
	ds_read_b128 v[70:73], v36 offset:16
	ds_read_b128 v[74:77], v59 offset:17408
	ds_read_b128 v[78:81], v59 offset:17424
	ds_read_b128 v[82:85], v59 offset:21760
	ds_read_b128 v[86:89], v59 offset:21776
	ds_read_b128 v[90:93], v36 offset:128
	ds_read_b128 v[94:97], v36 offset:144
	ds_read_b128 v[98:101], v59 offset:17536
	ds_read_b128 v[102:105], v59 offset:17552
	ds_read_b128 v[106:109], v59 offset:21888
	ds_read_b128 v[110:113], v59 offset:21904
	s_waitcnt lgkmcnt(0)
	s_barrier
	s_waitcnt vmcnt(6)
	ds_write_b128 v37, v[136:139]
	s_waitcnt vmcnt(5)
	ds_write2_b32 v61, v140, v141 offset1:68
	ds_write2_b32 v61, v142, v143 offset0:136 offset1:204
	ds_write_b128 v58, v[144:147]
	v_cvt_pk_bf16_f32 v6, v66, v67
	v_cvt_pk_bf16_f32 v7, v68, v69
	v_cvt_pk_bf16_f32 v8, v70, v71
	v_cvt_pk_bf16_f32 v9, v72, v73
	v_cvt_pk_bf16_f32 v18, v74, v75
	v_cvt_pk_bf16_f32 v19, v76, v77
	v_cvt_pk_bf16_f32 v20, v78, v79
	v_cvt_pk_bf16_f32 v21, v80, v81
	v_cvt_pk_bf16_f32 v22, v82, v83
	v_cvt_pk_bf16_f32 v23, v84, v85
	v_cvt_pk_bf16_f32 v24, v86, v87
	v_cvt_pk_bf16_f32 v25, v88, v89
	v_cvt_pk_bf16_f32 v66, v90, v91
	v_cvt_pk_bf16_f32 v67, v92, v93
	v_cvt_pk_bf16_f32 v68, v94, v95
	v_cvt_pk_bf16_f32 v69, v96, v97
	v_mfma_f32_16x16x32_bf16 v[10:13], v[6:9], v[18:21], v[10:13]
	v_cvt_pk_bf16_f32 v18, v98, v99
	v_cvt_pk_bf16_f32 v19, v100, v101
	v_cvt_pk_bf16_f32 v20, v102, v103
	v_mfma_f32_16x16x32_bf16 v[14:17], v[6:9], v[22:25], v[14:17]
	v_cvt_pk_bf16_f32 v21, v104, v105
	v_cvt_pk_bf16_f32 v22, v106, v107
	v_cvt_pk_bf16_f32 v23, v108, v109
	v_cvt_pk_bf16_f32 v24, v110, v111
	v_cvt_pk_bf16_f32 v25, v112, v113
	v_mfma_f32_16x16x32_bf16 v[6:9], v[66:69], v[18:21], v[10:13]
	v_mov_b32_e32 v3, 0
	v_mov_b32_e32 v4, 0
	v_mov_b32_e32 v5, 0
	v_mfma_f32_16x16x32_bf16 v[10:13], v[66:69], v[22:25], v[14:17]
	s_waitcnt vmcnt(4)
	ds_write2_b32 v60, v148, v149 offset1:68
	ds_write2_b32 v60, v150, v151 offset0:136 offset1:204
	s_waitcnt lgkmcnt(0)
	s_barrier
	s_and_saveexec_b64 s[6:7], vcc
	s_cbranch_execz .LBB0_56
	v_lshlrev_b64 v[2:3], 12, v[54:55]
	v_lshl_add_u64 v[2:3], s[4:5], 0, v[2:3]
	v_lshl_add_u64 v[2:3], v[2:3], 0, v[26:27]
.LBB0_56:
	s_or_b64 exec, exec, s[6:7]
	v_lshl_add_u64 v[14:15], v[52:53], 0, v[46:47]
	v_mov_b32_e32 v18, 0
	v_mov_b32_e32 v19, 0
	v_mov_b32_e32 v20, 0
	v_mov_b32_e32 v21, 0
	s_and_saveexec_b64 s[6:7], s[2:3]
	s_cbranch_execz .LBB0_58
	v_lshlrev_b64 v[18:19], 12, v[56:57]
	v_lshl_add_u64 v[18:19], s[4:5], 0, v[18:19]
	v_lshl_add_u64 v[18:19], v[18:19], 0, v[26:27]
.LBB0_58:
	s_or_b64 exec, exec, s[6:7]
	v_lshl_add_u64 v[22:23], v[52:53], 0, v[48:49]
	ds_read_b128 v[52:55], v36
	ds_read_b128 v[62:65], v36 offset:16
	ds_read_b128 v[66:69], v59 offset:17408
	ds_read_b128 v[70:73], v59 offset:17424
	ds_read_b128 v[74:77], v59 offset:21760
	ds_read_b128 v[78:81], v59 offset:21776
	ds_read_b128 v[82:85], v36 offset:128
	ds_read_b128 v[86:89], v36 offset:144
	ds_read_b128 v[90:93], v59 offset:17536
	ds_read_b128 v[94:97], v59 offset:17552
	ds_read_b128 v[98:101], v59 offset:21888
	ds_read_b128 v[102:105], v59 offset:21904
	s_waitcnt lgkmcnt(0)
	s_barrier
	s_waitcnt vmcnt(2)
	ds_write_b128 v37, v[152:155]
	s_waitcnt vmcnt(1)
	ds_write2_b32 v61, v156, v157 offset1:68
	ds_write2_b32 v61, v158, v159 offset0:136 offset1:204
	ds_write_b128 v58, v[160:163]
	v_cvt_pk_bf16_f32 v2, v52, v53
	v_cvt_pk_bf16_f32 v3, v54, v55
	v_cvt_pk_bf16_f32 v4, v62, v63
	v_cvt_pk_bf16_f32 v5, v64, v65
	v_cvt_pk_bf16_f32 v14, v66, v67
	v_cvt_pk_bf16_f32 v15, v68, v69
	v_cvt_pk_bf16_f32 v16, v70, v71
	v_cvt_pk_bf16_f32 v17, v72, v73
	v_cvt_pk_bf16_f32 v18, v74, v75
	v_cvt_pk_bf16_f32 v19, v76, v77
	v_cvt_pk_bf16_f32 v20, v78, v79
	v_cvt_pk_bf16_f32 v21, v80, v81
	v_cvt_pk_bf16_f32 v52, v82, v83
	v_cvt_pk_bf16_f32 v53, v84, v85
	v_cvt_pk_bf16_f32 v54, v86, v87
	v_cvt_pk_bf16_f32 v55, v88, v89
	v_mfma_f32_16x16x32_bf16 v[6:9], v[2:5], v[14:17], v[6:9]
	v_cvt_pk_bf16_f32 v14, v90, v91
	v_cvt_pk_bf16_f32 v15, v92, v93
	v_cvt_pk_bf16_f32 v16, v94, v95
	v_mfma_f32_16x16x32_bf16 v[2:5], v[2:5], v[18:21], v[10:13]
	v_cvt_pk_bf16_f32 v17, v96, v97
	s_lshl_b32 s0, s53, 8
	s_or_b32 s0, s0, s52
	v_cvt_pk_bf16_f32 v10, v98, v99
	v_cvt_pk_bf16_f32 v11, v100, v101
	v_cvt_pk_bf16_f32 v12, v102, v103
	v_cvt_pk_bf16_f32 v13, v104, v105
	v_mfma_f32_16x16x32_bf16 v[6:9], v[52:55], v[14:17], v[6:9]
	s_waitcnt vmcnt(0)
	ds_write2_b32 v60, v164, v165 offset1:68
	ds_write2_b32 v60, v166, v167 offset0:136 offset1:204
	v_mfma_f32_16x16x32_bf16 v[2:5], v[52:55], v[10:13], v[2:5]
	s_waitcnt lgkmcnt(0)
	s_barrier
	ds_read_b128 v[10:13], v36
	ds_read_b128 v[14:17], v36 offset:16
	ds_read_b128 v[18:21], v59 offset:17408
	ds_read_b128 v[22:25], v59 offset:17424
	ds_read_b128 v[52:55], v59 offset:21760
	ds_read_b128 v[60:63], v59 offset:21776
	ds_read_b128 v[64:67], v36 offset:128
	ds_read_b128 v[68:71], v36 offset:144
	ds_read_b128 v[72:75], v59 offset:17536
	ds_read_b128 v[76:79], v59 offset:17552
	ds_read_b128 v[80:83], v59 offset:21888
	ds_read_b128 v[84:87], v59 offset:21904
	s_waitcnt lgkmcnt(11)
	v_cvt_pk_bf16_f32 v10, v10, v11
	v_cvt_pk_bf16_f32 v11, v12, v13
	s_waitcnt lgkmcnt(10)
	v_cvt_pk_bf16_f32 v12, v14, v15
	v_cvt_pk_bf16_f32 v13, v16, v17
	s_waitcnt lgkmcnt(9)
	v_cvt_pk_bf16_f32 v14, v18, v19
	v_cvt_pk_bf16_f32 v15, v20, v21
	s_waitcnt lgkmcnt(8)
	v_cvt_pk_bf16_f32 v16, v22, v23
	v_cvt_pk_bf16_f32 v17, v24, v25
	s_waitcnt lgkmcnt(7)
	v_cvt_pk_bf16_f32 v18, v52, v53
	v_cvt_pk_bf16_f32 v19, v54, v55
	s_waitcnt lgkmcnt(6)
	v_cvt_pk_bf16_f32 v20, v60, v61
	v_cvt_pk_bf16_f32 v21, v62, v63
	s_waitcnt lgkmcnt(5)
	v_cvt_pk_bf16_f32 v22, v64, v65
	v_cvt_pk_bf16_f32 v23, v66, v67
	s_waitcnt lgkmcnt(4)
	v_cvt_pk_bf16_f32 v24, v68, v69
	v_cvt_pk_bf16_f32 v25, v70, v71
	v_mfma_f32_16x16x32_bf16 v[6:9], v[10:13], v[14:17], v[6:9]
	s_waitcnt lgkmcnt(3)
	v_cvt_pk_bf16_f32 v14, v72, v73
	v_cvt_pk_bf16_f32 v15, v74, v75
	s_waitcnt lgkmcnt(2)
	v_cvt_pk_bf16_f32 v16, v76, v77
	v_mfma_f32_16x16x32_bf16 v[2:5], v[10:13], v[18:21], v[2:5]
	v_cvt_pk_bf16_f32 v17, v78, v79
	s_waitcnt lgkmcnt(1)
	v_cvt_pk_bf16_f32 v10, v80, v81
	v_cvt_pk_bf16_f32 v11, v82, v83
	s_waitcnt lgkmcnt(0)
	v_cvt_pk_bf16_f32 v12, v84, v85
	v_cvt_pk_bf16_f32 v13, v86, v87
	v_mfma_f32_16x16x32_bf16 v[6:9], v[22:25], v[14:17], v[6:9]
	s_barrier
	v_mfma_f32_16x16x32_bf16 v[2:5], v[22:25], v[10:13], v[2:5]
	v_add_u32_e32 v12, s30, v33
	s_lshl_b32 s30, s0, 2
	v_lshl_add_u64 v[10:11], v[50:51], 0, s[30:31]
	v_cmp_gt_i32_e32 vcc, s60, v12
	v_ashrrev_i32_e32 v13, 31, v12
	s_and_saveexec_b64 s[2:3], vcc
	s_cbranch_execz .LBB0_60
	v_lshlrev_b64 v[14:15], 12, v[12:13]
	v_lshl_add_u64 v[14:15], v[10:11], 0, v[14:15]
	global_store_dword v[14:15], v6, off
